# plan A + grid barrier: drop the redundant write-back/invalidate pair of the last arriver of a group
# baseline (speedup 1.0000x reference)
.LBB0_59:
	s_or_b64 exec, exec, s[4:5]
	s_lshr_b32 s1, s11, 3
	s_waitcnt vmcnt(0)
	v_readfirstlane_b32 s4, v2
	s_mul_i32 s1, s1, s0
	s_nop 0
	v_add3_u32 v1, s4, v1, 1
	v_cmp_eq_u32_e32 vcc, s1, v1
	s_and_saveexec_b64 s[4:5], vcc
	s_cbranch_execz .LBB0_62
	s_mov_b64 s[6:7], exec
	v_mbcnt_lo_u32_b32 v1, s6, 0
	v_mbcnt_hi_u32_b32 v1, s7, v1
	v_cmp_eq_u32_e32 vcc, 0, v1
	s_and_b64 s[8:9], exec, vcc
	s_mov_b64 exec, s[8:9]
	s_cbranch_execz .LBB0_62
	s_bcnt1_i32_b64 s1, s[6:7]
	v_mov_b32_e32 v1, 0x1ebaa000
	v_mov_b32_e32 v2, s1
	global_atomic_add v1, v2, s[68:69] offset:256

.LBB0_562:
	s_or_b64 exec, exec, s[2:3]
	s_lshr_b32 s1, s11, 3
	s_waitcnt vmcnt(0)
	v_readfirstlane_b32 s2, v2
	s_mul_i32 s1, s1, s0
	s_nop 0
	v_add3_u32 v1, s2, v1, 1
	v_cmp_eq_u32_e32 vcc, s1, v1
	s_and_saveexec_b64 s[2:3], vcc
	s_cbranch_execz .LBB0_565
	s_mov_b64 s[6:7], exec
	v_mbcnt_lo_u32_b32 v1, s6, 0
	v_mbcnt_hi_u32_b32 v1, s7, v1
	v_cmp_eq_u32_e32 vcc, 0, v1
	s_and_b64 s[8:9], exec, vcc
	s_mov_b64 exec, s[8:9]
	s_cbranch_execz .LBB0_565
	s_bcnt1_i32_b64 s1, s[6:7]
	v_mov_b32_e32 v1, 0x1ebaa000
	v_mov_b32_e32 v2, s1
	global_atomic_add v1, v2, s[68:69] offset:256

.LBB0_723:
	s_or_b64 exec, exec, s[2:3]
	s_lshr_b32 s2, s11, 3
	s_waitcnt vmcnt(0)
	v_readfirstlane_b32 s3, v1
	s_mul_i32 s2, s2, s8
	s_nop 0
	v_add3_u32 v0, s3, v0, 1
	v_cmp_eq_u32_e32 vcc, s2, v0
	s_and_saveexec_b64 s[2:3], vcc
	s_cbranch_execz .LBB0_726
	s_mov_b64 s[4:5], exec
	v_mbcnt_lo_u32_b32 v0, s4, 0
	v_mbcnt_hi_u32_b32 v0, s5, v0
	v_cmp_eq_u32_e32 vcc, 0, v0
	s_and_b64 s[6:7], exec, vcc
	s_mov_b64 exec, s[6:7]
	s_cbranch_execz .LBB0_726
	s_bcnt1_i32_b64 s4, s[4:5]
	v_mov_b32_e32 v0, 0x1ebaa000
	v_mov_b32_e32 v1, s4
	global_atomic_add v0, v1, s[68:69] offset:256
